# v104 + retention workgroups also convert the first 2048 layer-1 w_in tiles in layer 0's mixer phase (copy loop run as a 64-workgroup grid); layer-1 copy phase skips them
# baseline (speedup 1.0000x reference)
.Lmy_a_entry:
	s_waitcnt vmcnt(0)
	v_mov_b32_e32 v8, v0
	s_mov_b64 s[6:7], s[70:71]
	s_load_dwordx2 s[4:5], s[6:7], 0xe0
	v_readlane_b32 s8, v253, 3
	v_readfirstlane_b32 s0, v8
	v_readlane_b32 s9, v253, 4
	v_and_b32_e32 v16, 63, v8
	s_cmp_eq_u32 s100, 1
	s_cbranch_scc1 .Lmy_a_zero
	s_cmp_eq_u32 s100, 6
	s_cbranch_scc1 .Lmy_a_zero
	s_cmp_eq_u32 s100, 0
	s_cbranch_scc0 .Lmy_a_keep
	s_cmpk_lg_i32 s3, 0x100
	s_cbranch_scc1 .Lmy_a_keep
	v_readlane_b32 s2, v255, 8
	s_nop 3
	s_cmp_eq_u32 s2, 1
	s_cbranch_scc0 .Lmy_a_keep

.LBB0_37:
	s_cmp_eq_u32 s100, 3
	s_cbranch_scc1 .Lmy_tr_dret
	v_readlane_b32 s0, v253, 5
	s_add_i32 s2, s30, s0
	s_movk_i32 s101, 0x4540
	s_cmp_eq_u32 s100, 1
	s_cbranch_scc1 .Lmy_a_def
	s_cmp_eq_u32 s100, 6
	s_cbranch_scc1 .Lmy_a_m6
	s_cmpk_lg_i32 s3, 0x100
	s_cbranch_scc1 .Lmy_a_it
	s_movk_i32 s101, 0x3440
	s_branch .Lmy_a_it
.Lmy_a_m6:
	s_add_i32 s76, s76, 0xffffff80
	s_movk_i32 s3, 64
	s_movk_i32 s96, 0x200
	s_lshl_b32 s2, s76, 3
	s_add_i32 s2, s2, s30
	s_movk_i32 s101, 0x800
	s_branch .Lmy_a_it

.Lmy_a_it:
	s_cmp_ge_i32 s2, s101
	s_waitcnt lgkmcnt(0)
	s_barrier
	s_cbranch_scc1 .LBB0_88
	s_load_dwordx2 s[8:9], s[6:7], 0x38
	v_readlane_b32 s12, v255, 8
	s_load_dwordx2 s[10:11], s[6:7], 0xc8
	s_nop 0
	s_load_dwordx2 s[6:7], s[6:7], 0xa8
	v_readlane_b32 s13, v255, 9
	s_mul_i32 s0, s12, 0xd080000
	s_mov_b32 s13, s89
	s_waitcnt lgkmcnt(0)
	s_add_u32 s42, s8, s0
	s_addc_u32 s43, s9, 0
	s_lshl_b64 s[8:9], s[12:13], 26
	s_add_u32 s44, s10, s8
	s_addc_u32 s45, s11, s9
	s_lshl_b64 s[8:9], s[12:13], 22
	s_add_u32 s46, s6, s8
	s_addc_u32 s47, s7, s9
	s_lshl_b64 s[6:7], s[12:13], 21
	s_add_u32 s6, s4, s6
	s_mov_b32 s0, s12
	s_addc_u32 s7, s5, s7
	v_writelane_b32 v255, s0, 8
	s_lshl_b64 s[8:9], s[12:13], 25
	s_add_u32 s8, s4, s8
	v_writelane_b32 v255, s1, 9
	s_mul_i32 s0, s30, 0x4400
	s_addc_u32 s9, s5, s9
	s_add_i32 s10, s0, 0
	v_lshrrev_b32_e32 v11, 4, v16
	v_mov_b32_e32 v2, s10
	s_movk_i32 s11, 0x110
	v_and_b32_e32 v3, 7, v8
	v_mad_u32_u24 v31, v11, s11, v2
	v_lshrrev_b32_e32 v42, 3, v16
	s_movk_i32 s11, 0x880
	v_lshlrev_b32_e32 v5, 2, v3
	v_mad_u32_u24 v4, v3, s11, v2
	v_xor_b32_e32 v6, v5, v42
	v_lshl_add_u32 v43, v6, 2, v4
	v_bitop3_b32 v6, v42, v5, 8 bitop3:0x36
	v_lshl_add_u32 v45, v6, 2, v4
	v_bitop3_b32 v6, v42, v5, 16 bitop3:0x36
	v_lshl_add_u32 v47, v6, 2, v4
	v_bitop3_b32 v6, v42, v5, 24 bitop3:0x36
	v_lshl_add_u32 v49, v6, 2, v4
	v_bitop3_b32 v6, v42, v5, 32 bitop3:0x36
	v_lshlrev_b32_e32 v12, 3, v16
	v_lshl_add_u32 v51, v6, 2, v4
	v_bitop3_b32 v6, v42, v5, 40 bitop3:0x36
	v_and_b32_e32 v12, 56, v12
	v_lshlrev_b32_e32 v194, 4, v3
	v_lshl_add_u32 v53, v6, 2, v4
	v_bitop3_b32 v6, v42, v5, 48 bitop3:0x36
	v_mul_u32_u24_e32 v14, 0x84, v12
	v_lshlrev_b32_e32 v12, 1, v12
	v_mov_b32_e32 v13, v195
	v_lshlrev_b32_e32 v15, 2, v42
	v_lshl_add_u32 v55, v6, 2, v4
	v_lshrrev_b32_e32 v6, 5, v16
	v_lshl_add_u64 v[12:13], s[4:5], 0, v[12:13]
	v_add3_u32 v58, s10, v14, v15
	v_lshl_add_u64 v[14:15], s[4:5], 0, v[194:195]
	s_mov_b64 s[4:5], 0x100000
	v_lshl_add_u64 v[2:3], s[6:7], 0, v[194:195]
	s_mov_b64 s[6:7], 0xab00000
	v_bitop3_b32 v5, v42, v5, 56 bitop3:0x36
	v_and_b32_e32 v17, 31, v8
	v_lshl_add_u64 v[14:15], v[14:15], 0, s[4:5]
	s_mul_i32 s4, s30, 0xfff2f800
	v_readlane_b32 s5, v254, 24
	v_mul_u32_u24_e32 v21, 0x84, v6
	v_and_b32_e32 v7, 15, v8
	v_lshl_add_u64 v[2:3], v[2:3], 0, s[6:7]
	v_or_b32_e32 v44, 8, v42
	v_or_b32_e32 v46, 16, v42
	v_or_b32_e32 v48, 24, v42
	v_lshl_add_u32 v57, v5, 2, v4
	v_lshl_add_u64 v[4:5], s[8:9], 0, v[194:195]
	s_mov_b64 s[6:7], 0x6b00000
	v_lshlrev_b32_e32 v19, 2, v17
	s_add_i32 s4, s4, s5
	v_or_b32_e32 v21, s0, v21
	s_mul_i32 s30, s30, 0xd0800
	s_mul_i32 s0, s76, 0x684000
	v_lshlrev_b32_e32 v9, 2, v7
	v_lshlrev_b32_e32 v34, 4, v7
	v_lshl_add_u64 v[4:5], v[4:5], 0, s[6:7]
	v_add_u32_e32 v10, s10, v19
	s_mov_b64 s[6:7], 0xaf00000
	v_lshlrev_b32_e32 v16, 12, v42
	v_lshlrev_b32_e32 v18, 12, v44
	v_lshlrev_b32_e32 v20, 12, v46
	v_lshlrev_b32_e32 v22, 12, v48
	v_cmp_lt_u32_e64 s[38:39], 7, v7
	v_mov_b32_e32 v7, s4
	s_movk_i32 s4, 0xcbe0
	v_add3_u32 v61, v21, v19, 0
	s_add_i32 s0, s0, s30
	v_mul_u32_u24_e32 v19, 0x3420, v6
	v_xor_b32_e32 v35, 16, v34
	v_xor_b32_e32 v36, 32, v34
	v_xor_b32_e32 v37, 48, v34
	v_xor_b32_e32 v38, 64, v34
	v_xor_b32_e32 v39, 0x50, v34
	v_xor_b32_e32 v40, 0x60, v34
	v_xor_b32_e32 v41, 0x70, v34
	v_or_b32_e32 v50, 32, v42
	v_or_b32_e32 v52, 40, v42
	v_or_b32_e32 v54, 48, v42
	v_or_b32_e32 v56, 56, v42
	v_or_b32_e32 v8, 0x1c00, v17
	v_lshl_add_u64 v[12:13], v[12:13], 0, s[6:7]
	v_subrev_u32_e32 v59, 32, v9
	v_mad_i32_i24 v60, v6, s4, v7
	v_mov_b32_e32 v7, v6
	v_add3_u32 v62, s0, v19, v17
	s_mov_b32 s8, 0
	v_lshlrev_b32_e32 v16, 1, v16
	v_lshlrev_b32_e32 v18, 1, v18
	v_lshlrev_b32_e32 v20, 1, v20
	v_lshlrev_b32_e32 v22, 1, v22
	s_cmp_eq_u32 s100, 0
	s_cbranch_scc0 .Lmy_a_k0
	s_cmpk_lg_i32 s3, 0x100
	s_cbranch_scc1 .Lmy_a_k0
	v_readlane_b32 s4, v255, 8
	s_nop 3
	s_cmp_eq_u32 s4, 1
	s_cbranch_scc0 .Lmy_a_k0
	s_branch .LBB0_40
.Lmy_a_k0:
	s_branch .LBB0_41
.LBB0_39:
	s_lshl_b32 s4, s0, 6
	s_cmp_gt_i32 s10, -1
	s_cselect_b64 vcc, -1, 0
	v_add_u32_e32 v19, s10, v59
	v_add_u32_e32 v21, s9, v9
	s_and_b64 s[40:41], vcc, s[38:39]
	v_cndmask_b32_e64 v26, v21, v19, s[40:41]
	v_or_b32_e32 v19, s4, v11
	v_ashrrev_i32_e32 v27, 31, v26
	v_lshl_add_u64 v[32:33], v[26:27], 2, s[42:43]
	v_or_b32_e32 v21, 4, v19
	v_mad_i64_i32 v[64:65], s[10:11], v21, s24, v[32:33]
	v_or_b32_e32 v21, 8, v19
	v_mad_i64_i32 v[68:69], s[10:11], v21, s24, v[32:33]
	v_or_b32_e32 v21, 12, v19
	v_mad_i64_i32 v[72:73], s[10:11], v21, s24, v[32:33]
	v_or_b32_e32 v21, 16, v19
	v_mad_i64_i32 v[76:77], s[10:11], v21, s24, v[32:33]
	v_or_b32_e32 v21, 20, v19
	v_mad_i64_i32 v[80:81], s[10:11], v21, s24, v[32:33]
	v_or_b32_e32 v21, 24, v19
	v_mad_i64_i32 v[84:85], s[10:11], v21, s24, v[32:33]
	v_or_b32_e32 v21, 28, v19
	v_mad_i64_i32 v[88:89], s[10:11], v21, s24, v[32:33]
	v_or_b32_e32 v21, 32, v19
	v_mad_i64_i32 v[92:93], s[10:11], v21, s24, v[32:33]
	v_or_b32_e32 v21, 36, v19
	v_mad_i64_i32 v[96:97], s[10:11], v21, s24, v[32:33]
	v_or_b32_e32 v21, 40, v19
	v_mad_i64_i32 v[100:101], s[10:11], v21, s24, v[32:33]
	v_or_b32_e32 v21, 44, v19
	v_mad_i64_i32 v[104:105], s[10:11], v21, s24, v[32:33]
	v_or_b32_e32 v21, 48, v19
	v_mad_i64_i32 v[26:27], s[10:11], v19, s24, v[32:33]
	v_mad_i64_i32 v[108:109], s[10:11], v21, s24, v[32:33]
	v_or_b32_e32 v21, 52, v19
	global_load_dwordx4 v[26:29], v[26:27], off nt
	s_nop 0
	global_load_dwordx4 v[64:67], v[64:65], off nt
	s_nop 0
	global_load_dwordx4 v[68:71], v[68:69], off nt
	s_nop 0
	global_load_dwordx4 v[72:75], v[72:73], off nt
	s_nop 0
	global_load_dwordx4 v[76:79], v[76:77], off nt
	s_nop 0
	global_load_dwordx4 v[80:83], v[80:81], off nt
	s_nop 0
	global_load_dwordx4 v[84:87], v[84:85], off nt
	s_nop 0
	global_load_dwordx4 v[88:91], v[88:89], off nt
	s_nop 0
	global_load_dwordx4 v[92:95], v[92:93], off nt
	s_nop 0
	global_load_dwordx4 v[96:99], v[96:97], off nt
	s_nop 0
	global_load_dwordx4 v[100:103], v[100:101], off nt
	s_nop 0
	global_load_dwordx4 v[104:107], v[104:105], off nt
	v_mad_i64_i32 v[112:113], s[10:11], v21, s24, v[32:33]
	v_or_b32_e32 v21, 56, v19
	global_load_dwordx4 v[108:111], v[108:109], off nt
	s_nop 0
	global_load_dwordx4 v[112:115], v[112:113], off nt
	v_mad_i64_i32 v[116:117], s[10:11], v21, s24, v[32:33]
	v_or_b32_e32 v19, 60, v19
	v_mad_i64_i32 v[32:33], s[10:11], v19, s24, v[32:33]
	global_load_dwordx4 v[116:119], v[116:117], off nt
	s_nop 0
	global_load_dwordx4 v[120:123], v[32:33], off nt
	v_add_u32_e32 v19, v31, v34
	v_add_u32_e32 v21, v31, v35
	v_add_u32_e32 v23, v31, v36
	v_add_u32_e32 v25, v31, v37
	v_add_u32_e32 v30, v31, v38
	v_add_u32_e32 v32, v31, v39
	s_ashr_i32 s5, s4, 31
	s_waitcnt vmcnt(15)
	ds_write_b128 v19, v[26:29]
	s_waitcnt vmcnt(14)
	ds_write_b128 v19, v[64:67] offset:1088
	s_waitcnt vmcnt(13)
	ds_write_b128 v21, v[68:71] offset:2176
	s_waitcnt vmcnt(12)
	ds_write_b128 v21, v[72:75] offset:3264
	s_waitcnt vmcnt(11)
	ds_write_b128 v23, v[76:79] offset:4352
	s_waitcnt vmcnt(10)
	ds_write_b128 v23, v[80:83] offset:5440
	s_waitcnt vmcnt(9)
	ds_write_b128 v25, v[84:87] offset:6528
	s_waitcnt vmcnt(8)
	ds_write_b128 v25, v[88:91] offset:7616
	s_waitcnt vmcnt(7)
	ds_write_b128 v30, v[92:95] offset:8704
	s_waitcnt vmcnt(6)
	ds_write_b128 v30, v[96:99] offset:9792
	s_waitcnt vmcnt(5)
	ds_write_b128 v32, v[100:103] offset:10880
	s_waitcnt vmcnt(4)
	ds_write_b128 v32, v[104:107] offset:11968
	v_add_u32_e32 v19, v31, v40
	s_waitcnt vmcnt(3)
	ds_write_b128 v19, v[108:111] offset:13056
	s_waitcnt vmcnt(2)
	ds_write_b128 v19, v[112:115] offset:14144
	v_add_u32_e32 v19, v31, v41
	s_waitcnt vmcnt(1)
	ds_write_b128 v19, v[116:119] offset:15232
	s_waitcnt vmcnt(0)
	ds_write_b128 v19, v[120:123] offset:16320
	s_waitcnt lgkmcnt(0)
	ds_read2_b32 v[28:29], v43 offset1:68
	ds_read2_b32 v[26:27], v43 offset0:136 offset1:204
	v_cndmask_b32_e32 v30, v24, v17, vcc
	v_add_u32_e32 v17, 0x400, v43
	ds_read2_b32 v[66:67], v17 offset0:16 offset1:84
	ds_read2_b32 v[68:69], v17 offset0:152 offset1:220
	s_waitcnt lgkmcnt(3)
	v_mov_b32_e32 v64, v28
	s_waitcnt lgkmcnt(2)
	v_mov_b32_e32 v65, v26
	v_mov_b32_e32 v26, v29
	v_pk_mul_f32 v[64:65], v[24:25], v[64:65] op_sel_hi:[0,1]
	v_pk_mul_f32 v[26:27], v[24:25], v[26:27] op_sel_hi:[0,1]
	s_waitcnt lgkmcnt(1)
	v_mov_b32_e32 v28, v66
	s_waitcnt lgkmcnt(0)
	v_mov_b32_e32 v29, v68
	v_mov_b32_e32 v68, v67
	v_pk_mul_f32 v[28:29], v[24:25], v[28:29] op_sel_hi:[0,1]
	v_pk_mul_f32 v[66:67], v[24:25], v[68:69] op_sel_hi:[0,1]
	v_bfe_u32 v21, v27, 16, 1
	v_bfe_u32 v23, v26, 16, 1
	v_bfe_u32 v25, v64, 16, 1
	v_add3_u32 v23, v26, v23, s22
	v_add3_u32 v21, v27, v21, s22
	v_bfe_u32 v26, v65, 16, 1
	v_bfe_u32 v27, v28, 16, 1
	v_bfe_u32 v63, v29, 16, 1
	v_add3_u32 v25, v64, v25, s22
	v_or_b32_e32 v64, s6, v42
	v_bfe_u32 v17, v67, 16, 1
	v_bfe_u32 v19, v66, 16, 1
	v_add3_u32 v29, v29, v63, s22
	v_add3_u32 v27, v28, v27, s22
	v_add3_u32 v26, v65, v26, s22
	v_ashrrev_i32_e32 v65, 31, v64
	v_lshl_add_u64 v[32:33], s[4:5], 1, v[14:15]
	v_add3_u32 v19, v66, v19, s22
	v_add3_u32 v17, v67, v17, s22
	v_lshrrev_b32_e32 v25, 16, v25
	v_lshrrev_b32_e32 v26, 16, v26
	v_lshrrev_b32_e32 v27, 16, v27
	v_lshrrev_b32_e32 v28, 16, v29
	v_lshlrev_b64 v[64:65], 13, v[64:65]
	v_and_or_b32 v29, v17, s23, v28
	v_and_or_b32 v28, v19, s23, v27
	v_and_or_b32 v27, v21, s23, v26
	v_and_or_b32 v26, v23, s23, v25
	v_lshl_add_u64 v[64:65], v[32:33], 0, v[64:65]
	ds_read2_b32 v[66:67], v45 offset1:68
	ds_read2_b32 v[68:69], v45 offset0:136 offset1:204
	global_store_dwordx4 v[64:65], v[26:29], off
	v_add_u32_e32 v17, 0x400, v45
	ds_read2_b32 v[28:29], v17 offset0:16 offset1:84
	ds_read2_b32 v[64:65], v17 offset0:152 offset1:220
	s_waitcnt lgkmcnt(3)
	v_mov_b32_e32 v26, v66
	s_waitcnt lgkmcnt(2)
	v_mov_b32_e32 v27, v68
	v_mov_b32_e32 v68, v67
	v_pk_mul_f32 v[66:67], v[24:25], v[68:69] op_sel_hi:[0,1]
	s_waitcnt lgkmcnt(0)
	v_mov_b32_e32 v69, v64
	v_mov_b32_e32 v64, v29
	v_mov_b32_e32 v68, v28
	v_pk_mul_f32 v[28:29], v[24:25], v[64:65] op_sel_hi:[0,1]
	v_pk_mul_f32 v[26:27], v[24:25], v[26:27] op_sel_hi:[0,1]
	v_pk_mul_f32 v[68:69], v[24:25], v[68:69] op_sel_hi:[0,1]
	v_bfe_u32 v17, v29, 16, 1
	v_bfe_u32 v19, v28, 16, 1
	v_add3_u32 v19, v28, v19, s22
	v_add3_u32 v17, v29, v17, s22
	v_bfe_u32 v25, v26, 16, 1
	v_bfe_u32 v28, v27, 16, 1
	v_bfe_u32 v29, v68, 16, 1
	v_bfe_u32 v63, v69, 16, 1
	v_or_b32_e32 v64, s6, v44
	v_bfe_u32 v21, v67, 16, 1
	v_bfe_u32 v23, v66, 16, 1
	v_add3_u32 v63, v69, v63, s22
	v_add3_u32 v29, v68, v29, s22
	v_add3_u32 v27, v27, v28, s22
	v_add3_u32 v25, v26, v25, s22
	v_ashrrev_i32_e32 v65, 31, v64
	v_add3_u32 v23, v66, v23, s22
	v_add3_u32 v21, v67, v21, s22
	v_lshrrev_b32_e32 v25, 16, v25
	v_lshrrev_b32_e32 v26, 16, v27
	v_lshrrev_b32_e32 v27, 16, v29
	v_lshrrev_b32_e32 v28, 16, v63
	v_lshlrev_b64 v[64:65], 13, v[64:65]
	v_and_or_b32 v29, v17, s23, v28
	v_and_or_b32 v28, v19, s23, v27
	v_and_or_b32 v27, v21, s23, v26
	v_and_or_b32 v26, v23, s23, v25
	v_lshl_add_u64 v[64:65], v[32:33], 0, v[64:65]
	ds_read2_b32 v[66:67], v47 offset1:68
	ds_read2_b32 v[68:69], v47 offset0:136 offset1:204
	global_store_dwordx4 v[64:65], v[26:29], off
	v_add_u32_e32 v17, 0x400, v47
	ds_read2_b32 v[28:29], v17 offset0:16 offset1:84
	ds_read2_b32 v[64:65], v17 offset0:152 offset1:220
	s_waitcnt lgkmcnt(3)
	v_mov_b32_e32 v26, v66
	s_waitcnt lgkmcnt(2)
	v_mov_b32_e32 v27, v68
	v_mov_b32_e32 v68, v67
	v_pk_mul_f32 v[66:67], v[24:25], v[68:69] op_sel_hi:[0,1]
	s_waitcnt lgkmcnt(0)
	v_mov_b32_e32 v69, v64
	v_mov_b32_e32 v64, v29
	v_mov_b32_e32 v68, v28
	v_pk_mul_f32 v[28:29], v[24:25], v[64:65] op_sel_hi:[0,1]
	v_pk_mul_f32 v[26:27], v[24:25], v[26:27] op_sel_hi:[0,1]
	v_pk_mul_f32 v[68:69], v[24:25], v[68:69] op_sel_hi:[0,1]
	v_bfe_u32 v17, v29, 16, 1
	v_bfe_u32 v19, v28, 16, 1
	v_add3_u32 v19, v28, v19, s22
	v_add3_u32 v17, v29, v17, s22
	v_bfe_u32 v25, v26, 16, 1
	v_bfe_u32 v28, v27, 16, 1
	v_bfe_u32 v29, v68, 16, 1
	v_bfe_u32 v63, v69, 16, 1
	v_or_b32_e32 v64, s6, v46
	v_bfe_u32 v21, v67, 16, 1
	v_bfe_u32 v23, v66, 16, 1
	v_add3_u32 v63, v69, v63, s22
	v_add3_u32 v29, v68, v29, s22
	v_add3_u32 v27, v27, v28, s22
	v_add3_u32 v25, v26, v25, s22
	v_ashrrev_i32_e32 v65, 31, v64
	v_add3_u32 v23, v66, v23, s22
	v_add3_u32 v21, v67, v21, s22
	v_lshrrev_b32_e32 v25, 16, v25
	v_lshrrev_b32_e32 v26, 16, v27
	v_lshrrev_b32_e32 v27, 16, v29
	v_lshrrev_b32_e32 v28, 16, v63
	v_lshlrev_b64 v[64:65], 13, v[64:65]
	v_and_or_b32 v29, v17, s23, v28
	v_and_or_b32 v28, v19, s23, v27
	v_and_or_b32 v27, v21, s23, v26
	v_and_or_b32 v26, v23, s23, v25
	v_lshl_add_u64 v[64:65], v[32:33], 0, v[64:65]
	ds_read2_b32 v[66:67], v49 offset1:68
	ds_read2_b32 v[68:69], v49 offset0:136 offset1:204
	global_store_dwordx4 v[64:65], v[26:29], off
	v_add_u32_e32 v17, 0x400, v49
	ds_read2_b32 v[28:29], v17 offset0:16 offset1:84
	ds_read2_b32 v[64:65], v17 offset0:152 offset1:220
	s_waitcnt lgkmcnt(3)
	v_mov_b32_e32 v26, v66
	s_waitcnt lgkmcnt(2)
	v_mov_b32_e32 v27, v68
	v_mov_b32_e32 v68, v67
	v_pk_mul_f32 v[66:67], v[24:25], v[68:69] op_sel_hi:[0,1]
	s_waitcnt lgkmcnt(1)
	v_mov_b32_e32 v68, v28
	s_waitcnt lgkmcnt(0)
	v_mov_b32_e32 v69, v64
	v_mov_b32_e32 v64, v29
	v_pk_mul_f32 v[26:27], v[24:25], v[26:27] op_sel_hi:[0,1]
	v_pk_mul_f32 v[68:69], v[24:25], v[68:69] op_sel_hi:[0,1]
	v_pk_mul_f32 v[24:25], v[24:25], v[64:65] op_sel_hi:[0,1]
	v_bfe_u32 v19, v24, 16, 1
	v_bfe_u32 v28, v68, 16, 1
	v_bfe_u32 v17, v25, 16, 1
	v_add3_u32 v19, v24, v19, s22
	v_bfe_u32 v24, v26, 16, 1
	v_bfe_u32 v29, v69, 16, 1
	v_add3_u32 v28, v68, v28, s22
	v_add3_u32 v17, v25, v17, s22
	v_bfe_u32 v25, v27, 16, 1
	v_add3_u32 v29, v69, v29, s22
	v_add3_u32 v24, v26, v24, s22
	v_lshrrev_b32_e32 v26, 16, v28
	v_or_b32_e32 v28, s6, v48
	v_bfe_u32 v21, v67, 16, 1
	v_bfe_u32 v23, v66, 16, 1
	v_add3_u32 v25, v27, v25, s22
	v_lshrrev_b32_e32 v27, 16, v29
	v_ashrrev_i32_e32 v29, 31, v28
	v_add3_u32 v23, v66, v23, s22
	v_add3_u32 v21, v67, v21, s22
	v_lshrrev_b32_e32 v24, 16, v24
	v_lshrrev_b32_e32 v25, 16, v25
	v_lshlrev_b64 v[28:29], 13, v[28:29]
	v_and_or_b32 v27, v17, s23, v27
	v_and_or_b32 v26, v19, s23, v26
	v_and_or_b32 v25, v21, s23, v25
	v_and_or_b32 v24, v23, s23, v24
	v_lshl_add_u64 v[28:29], v[32:33], 0, v[28:29]
	ds_read2_b32 v[64:65], v51 offset1:68
	ds_read2_b32 v[66:67], v51 offset0:136 offset1:204
	global_store_dwordx4 v[28:29], v[24:27], off
	v_add_u32_e32 v17, 0x400, v51
	ds_read2_b32 v[26:27], v17 offset0:16 offset1:84
	ds_read2_b32 v[28:29], v17 offset0:152 offset1:220
	s_waitcnt lgkmcnt(3)
	v_mov_b32_e32 v24, v64
	s_waitcnt lgkmcnt(2)
	v_mov_b32_e32 v25, v66
	v_mov_b32_e32 v66, v65
	v_pk_mul_f32 v[64:65], v[30:31], v[66:67] op_sel_hi:[0,1]
	s_waitcnt lgkmcnt(1)
	v_mov_b32_e32 v66, v26
	s_waitcnt lgkmcnt(0)
	v_mov_b32_e32 v67, v28
	v_mov_b32_e32 v28, v27
	v_pk_mul_f32 v[66:67], v[30:31], v[66:67] op_sel_hi:[0,1]
	v_pk_mul_f32 v[26:27], v[30:31], v[28:29] op_sel_hi:[0,1]
	v_pk_mul_f32 v[24:25], v[30:31], v[24:25] op_sel_hi:[0,1]
	v_bfe_u32 v19, v26, 16, 1
	v_bfe_u32 v28, v66, 16, 1
	v_bfe_u32 v17, v27, 16, 1
	v_add3_u32 v19, v26, v19, s22
	v_bfe_u32 v26, v24, 16, 1
	v_bfe_u32 v29, v67, 16, 1
	v_add3_u32 v28, v66, v28, s22
	v_add3_u32 v17, v27, v17, s22
	v_bfe_u32 v27, v25, 16, 1
	v_add3_u32 v29, v67, v29, s22
	v_add3_u32 v24, v24, v26, s22
	v_lshrrev_b32_e32 v26, 16, v28
	v_or_b32_e32 v28, s6, v50
	v_bfe_u32 v21, v65, 16, 1
	v_bfe_u32 v23, v64, 16, 1
	v_add3_u32 v25, v25, v27, s22
	v_lshrrev_b32_e32 v27, 16, v29
	v_ashrrev_i32_e32 v29, 31, v28
	v_add3_u32 v23, v64, v23, s22
	v_add3_u32 v21, v65, v21, s22
	v_lshrrev_b32_e32 v24, 16, v24
	v_lshrrev_b32_e32 v25, 16, v25
	v_lshlrev_b64 v[28:29], 13, v[28:29]
	v_and_or_b32 v27, v17, s23, v27
	v_and_or_b32 v26, v19, s23, v26
	v_and_or_b32 v25, v21, s23, v25
	v_and_or_b32 v24, v23, s23, v24
	v_lshl_add_u64 v[28:29], v[32:33], 0, v[28:29]
	ds_read2_b32 v[64:65], v53 offset1:68
	ds_read2_b32 v[66:67], v53 offset0:136 offset1:204
	global_store_dwordx4 v[28:29], v[24:27], off
	v_add_u32_e32 v17, 0x400, v53
	ds_read2_b32 v[26:27], v17 offset0:16 offset1:84
	ds_read2_b32 v[28:29], v17 offset0:152 offset1:220
	s_waitcnt lgkmcnt(3)
	v_mov_b32_e32 v24, v64
	s_waitcnt lgkmcnt(2)
	v_mov_b32_e32 v25, v66
	v_mov_b32_e32 v66, v65
	v_pk_mul_f32 v[64:65], v[30:31], v[66:67] op_sel_hi:[0,1]
	s_waitcnt lgkmcnt(1)
	v_mov_b32_e32 v66, v26
	s_waitcnt lgkmcnt(0)
	v_mov_b32_e32 v67, v28
	v_mov_b32_e32 v28, v27
	v_pk_mul_f32 v[66:67], v[30:31], v[66:67] op_sel_hi:[0,1]
	v_pk_mul_f32 v[26:27], v[30:31], v[28:29] op_sel_hi:[0,1]
	v_pk_mul_f32 v[24:25], v[30:31], v[24:25] op_sel_hi:[0,1]
	v_bfe_u32 v19, v26, 16, 1
	v_bfe_u32 v28, v66, 16, 1
	v_bfe_u32 v17, v27, 16, 1
	v_add3_u32 v19, v26, v19, s22
	v_bfe_u32 v26, v24, 16, 1
	v_bfe_u32 v29, v67, 16, 1
	v_add3_u32 v28, v66, v28, s22
	v_add3_u32 v17, v27, v17, s22
	v_bfe_u32 v27, v25, 16, 1
	v_add3_u32 v29, v67, v29, s22
	v_add3_u32 v24, v24, v26, s22
	v_lshrrev_b32_e32 v26, 16, v28
	v_or_b32_e32 v28, s6, v52
	v_bfe_u32 v21, v65, 16, 1
	v_bfe_u32 v23, v64, 16, 1
	v_add3_u32 v25, v25, v27, s22
	v_lshrrev_b32_e32 v27, 16, v29
	v_ashrrev_i32_e32 v29, 31, v28
	v_add3_u32 v23, v64, v23, s22
	v_add3_u32 v21, v65, v21, s22
	v_lshrrev_b32_e32 v24, 16, v24
	v_lshrrev_b32_e32 v25, 16, v25
	v_lshlrev_b64 v[28:29], 13, v[28:29]
	v_and_or_b32 v27, v17, s23, v27
	v_and_or_b32 v26, v19, s23, v26
	v_and_or_b32 v25, v21, s23, v25
	v_and_or_b32 v24, v23, s23, v24
	v_lshl_add_u64 v[28:29], v[32:33], 0, v[28:29]
	ds_read2_b32 v[64:65], v55 offset1:68
	ds_read2_b32 v[66:67], v55 offset0:136 offset1:204
	global_store_dwordx4 v[28:29], v[24:27], off
	v_add_u32_e32 v17, 0x400, v55
	ds_read2_b32 v[26:27], v17 offset0:16 offset1:84
	ds_read2_b32 v[28:29], v17 offset0:152 offset1:220
	s_waitcnt lgkmcnt(3)
	v_mov_b32_e32 v24, v64
	s_waitcnt lgkmcnt(2)
	v_mov_b32_e32 v25, v66
	v_mov_b32_e32 v66, v65
	v_pk_mul_f32 v[64:65], v[30:31], v[66:67] op_sel_hi:[0,1]
	s_waitcnt lgkmcnt(1)
	v_mov_b32_e32 v66, v26
	s_waitcnt lgkmcnt(0)
	v_mov_b32_e32 v67, v28
	v_mov_b32_e32 v28, v27
	v_pk_mul_f32 v[66:67], v[30:31], v[66:67] op_sel_hi:[0,1]
	v_pk_mul_f32 v[26:27], v[30:31], v[28:29] op_sel_hi:[0,1]
	v_pk_mul_f32 v[24:25], v[30:31], v[24:25] op_sel_hi:[0,1]
	v_bfe_u32 v19, v26, 16, 1
	v_bfe_u32 v28, v66, 16, 1
	v_bfe_u32 v17, v27, 16, 1
	v_add3_u32 v19, v26, v19, s22
	v_bfe_u32 v26, v24, 16, 1
	v_bfe_u32 v29, v67, 16, 1
	v_add3_u32 v28, v66, v28, s22
	v_add3_u32 v17, v27, v17, s22
	v_bfe_u32 v27, v25, 16, 1
	v_add3_u32 v29, v67, v29, s22
	v_add3_u32 v24, v24, v26, s22
	v_lshrrev_b32_e32 v26, 16, v28
	v_or_b32_e32 v28, s6, v54
	v_bfe_u32 v21, v65, 16, 1
	v_bfe_u32 v23, v64, 16, 1
	v_add3_u32 v25, v25, v27, s22
	v_lshrrev_b32_e32 v27, 16, v29
	v_ashrrev_i32_e32 v29, 31, v28
	v_add3_u32 v23, v64, v23, s22
	v_add3_u32 v21, v65, v21, s22
	v_lshrrev_b32_e32 v24, 16, v24
	v_lshrrev_b32_e32 v25, 16, v25
	v_lshlrev_b64 v[28:29], 13, v[28:29]
	v_and_or_b32 v27, v17, s23, v27
	v_and_or_b32 v26, v19, s23, v26
	v_and_or_b32 v25, v21, s23, v25
	v_and_or_b32 v24, v23, s23, v24
	v_lshl_add_u64 v[28:29], v[32:33], 0, v[28:29]
	ds_read2_b32 v[64:65], v57 offset1:68
	ds_read2_b32 v[66:67], v57 offset0:136 offset1:204
	global_store_dwordx4 v[28:29], v[24:27], off
	v_add_u32_e32 v17, 0x400, v57
	ds_read2_b32 v[26:27], v17 offset0:16 offset1:84
	ds_read2_b32 v[28:29], v17 offset0:152 offset1:220
	s_waitcnt lgkmcnt(3)
	v_mov_b32_e32 v24, v64
	s_waitcnt lgkmcnt(2)
	v_mov_b32_e32 v25, v66
	v_mov_b32_e32 v66, v65
	v_pk_mul_f32 v[64:65], v[30:31], v[66:67] op_sel_hi:[0,1]
	s_waitcnt lgkmcnt(1)
	v_mov_b32_e32 v66, v26
	s_waitcnt lgkmcnt(0)
	v_mov_b32_e32 v67, v28
	v_mov_b32_e32 v28, v27
	v_pk_mul_f32 v[66:67], v[30:31], v[66:67] op_sel_hi:[0,1]
	v_pk_mul_f32 v[26:27], v[30:31], v[28:29] op_sel_hi:[0,1]
	v_pk_mul_f32 v[24:25], v[30:31], v[24:25] op_sel_hi:[0,1]
	v_bfe_u32 v19, v26, 16, 1
	v_bfe_u32 v28, v66, 16, 1
	v_bfe_u32 v17, v27, 16, 1
	v_add3_u32 v19, v26, v19, s22
	v_bfe_u32 v26, v24, 16, 1
	v_bfe_u32 v29, v67, 16, 1
	v_add3_u32 v28, v66, v28, s22
	v_add3_u32 v17, v27, v17, s22
	v_bfe_u32 v27, v25, 16, 1
	v_add3_u32 v29, v67, v29, s22
	v_add3_u32 v24, v24, v26, s22
	v_lshrrev_b32_e32 v26, 16, v28
	v_or_b32_e32 v28, s6, v56
	v_bfe_u32 v21, v65, 16, 1
	v_bfe_u32 v23, v64, 16, 1
	v_add3_u32 v25, v25, v27, s22
	v_lshrrev_b32_e32 v27, 16, v29
	v_ashrrev_i32_e32 v29, 31, v28
	v_add3_u32 v23, v64, v23, s22
	v_add3_u32 v21, v65, v21, s22
	v_lshrrev_b32_e32 v24, 16, v24
	v_lshrrev_b32_e32 v25, 16, v25
	v_lshlrev_b64 v[28:29], 13, v[28:29]
	v_and_or_b32 v27, v17, s23, v27
	v_and_or_b32 v26, v19, s23, v26
	v_and_or_b32 v25, v21, s23, v25
	v_and_or_b32 v24, v23, s23, v24
	v_lshl_add_u64 v[28:29], v[32:33], 0, v[28:29]
	global_store_dwordx4 v[28:29], v[24:27], off
	s_waitcnt lgkmcnt(0)

.LBB0_88:
	s_cmp_eq_u32 s100, 6
	s_cbranch_scc0 .Lmy_a_n6
	s_movk_i32 s3, 0x100
	s_add_i32 s76, s76, 0x80
	v_readlane_b32 s96, v254, 60
	s_branch .Lmy_tr_dret2

.Lpb_next:
	s_add_i32 s65, s65, s3
	s_cmpk_lt_i32 s65, 0x440
	s_cbranch_scc1 .Lpb_loop
	s_branch .LBB0_178
	s_nop 0
	s_nop 0
	s_nop 0
	s_nop 0
	s_nop 0
	s_nop 0
	s_nop 0
	s_nop 0
	s_nop 0
	s_nop 0
	s_nop 0
	s_nop 0
	s_nop 0
	s_nop 0
	s_nop 0
	s_nop 0
	s_nop 0
	s_nop 0
	s_nop 0
	s_nop 0
	s_nop 0
	s_branch .LBB0_178
	s_nop 0
	s_nop 0
	s_nop 0
	s_nop 0
	s_nop 0
	s_nop 0
	s_nop 0
	s_nop 0
	s_nop 0
	s_nop 0
	s_nop 0
	s_nop 0
	s_nop 0
	s_nop 0
	s_nop 0
	s_nop 0
	s_nop 0
	s_nop 0
.LBB0_178:
	v_readlane_b32 s0, v255, 10
	v_readlane_b32 s60, v255, 0
	s_add_i32 s0, s0, 2
	v_readlane_b32 s63, v255, 3
	v_readlane_b32 s62, v255, 2
	s_cmp_ge_i32 s0, s63
	s_barrier
	v_readlane_b32 s61, v255, 1
	s_cbranch_scc1 .LBB0_190
	s_waitcnt vmcnt(0)
	s_barrier
	s_mov_b64 s[4:5], exec
	v_readlane_b32 s6, v254, 56
	v_readlane_b32 s7, v254, 57
	v_readlane_b32 s60, v255, 6
	s_and_b64 s[6:7], s[4:5], s[6:7]
	v_readlane_b32 s61, v255, 7
	s_mov_b64 exec, s[6:7]
	s_cbranch_execz .LBB0_228
	v_readlane_b32 s2, v253, 2
	s_waitcnt vmcnt(0) expcnt(0) lgkmcnt(0)
	s_nop 0
	v_mov_b32_e32 v2, s2
	ds_read_b32 v4, v2
	ds_read_b32 v2, v2 offset:4
	s_waitcnt lgkmcnt(1)
	v_cmp_ne_u32_e32 vcc, 0, v4
	s_cbranch_vccnz .LBB0_196
	v_readlane_b32 s8, v253, 0
	v_readlane_b32 s9, v253, 1
	s_load_dwordx2 s[6:7], s[8:9], 0x4
	s_mov_b32 s12, 1
	s_waitcnt lgkmcnt(0)
	s_mul_i32 s2, s6, s3
	s_mul_i32 s2, s2, s7
	s_branch .LBB0_183

.Lmy_d_ret:
	s_mov_b32 s100, 6
	s_branch .Lmy_tr_acall
